# out-proj split-K tail removed: its 32 sample-row tiles now run inside the following in-proj GEMM phase (workgroups 96-127 first), flag-synchronised
# baseline (speedup 1.0000x reference)
; #define LAS __attribute__((address_space(3)))
; __device__ __forceinline__ unsigned xb_add(unsigned* p, unsigned v) { return __hip_atomic_fetch_add(p, v, __ATOMIC_RELAXED, __HIP_MEMORY_SCOPE_AGENT); }
; __device__ __forceinline__ unsigned xb_xcc_id() { return (unsigned)__builtin_amdgcn_s_getreg((3 << 11) | 20) & 0xFu; }
; __device__ __forceinline__ XcdBarrier xcd_barrier_post(unsigned* bar, volatile LAS unsigned* st) {
;     XcdBarrier b; b.bar = bar; b.x = xb_xcc_id(); b.st = st;
;     if (threadIdx.x == 0) (void)xb_add(&bar[XB_XCNT(b.x)], 1u);
;     return b;
; }
; __global__ void __launch_bounds__(NTHR) mega(Params p) {
;     extern __shared__ __attribute__((aligned(16))) unsigned char lds_raw[];
;     LAS unsigned char* L = (LAS unsigned char*)lds_raw;
;     cg::grid_group grid = cg::this_grid();
;     unsigned char* ws = p.ws;
;     const int lo = p.ph_lo, hi = p.ph_hi;
;     LAS unsigned* stw = (LAS unsigned*)(L + (LDS_BYTES - 16));
;     if (threadIdx.x < 4) stw[threadIdx.x] = 0u;
;     __syncthreads();
;     const XcdBarrier xb = xcd_barrier_post((unsigned*)(ws + WS_BAR), (volatile LAS unsigned*)stw);
_Z4mega6Params:
	s_load_dwordx8 s[40:47], s[0:1], 0xc0
	s_load_dwordx2 s[94:95], s[0:1], 0xe0
	s_add_u32 s6, s0, 0xe0
	v_and_b32_e32 v136, 0x3ff, v0
	s_addc_u32 s7, s1, 0
	v_cmp_gt_u32_e32 vcc, 4, v136
	s_and_saveexec_b64 s[4:5], vcc
	v_lshl_add_u32 v1, v136, 2, 0
	v_add_u32_e32 v1, 0x26ff0, v1
	v_mov_b32_e32 v2, 0
	ds_write_b32 v1, v2
	s_or_b64 exec, exec, s[4:5]
	s_load_dword s3, s[0:1], 0xe8
	s_waitcnt lgkmcnt(0)
	s_barrier
	s_mov_b32 s101, 0
	s_add_u32 s92, s44, 0x1f70e000
	v_writelane_b32 v250, s3, 0
	s_getreg_b32 s3, hwreg(HW_REG_XCC_ID, 0, 4)
	s_addc_u32 s93, s45, 0
	s_and_b32 s3, s3, 15
	v_writelane_b32 v250, s3, 1
	v_cmp_eq_u32_e64 s[8:9], 0, v136
	s_mov_b64 s[4:5], exec
	s_nop 0
	v_writelane_b32 v250, s8, 2
	s_nop 1
	v_writelane_b32 v250, s9, 3
	s_and_b64 s[8:9], s[4:5], s[8:9]
	s_mov_b64 exec, s[8:9]
	s_cbranch_execz .LBB0_5
	s_mov_b64 s[8:9], exec
	v_mbcnt_lo_u32_b32 v1, s8, 0
	v_mbcnt_hi_u32_b32 v1, s9, v1
	v_cmp_eq_u32_e32 vcc, 0, v1
	s_and_b64 s[10:11], exec, vcc
	s_mov_b64 exec, s[10:11]
	s_cbranch_execz .LBB0_5
	v_readlane_b32 s3, v250, 1
	s_lshl_b32 s3, s3, 8
	s_bcnt1_i32_b64 s8, s[8:9]
	v_mov_b32_e32 v1, s3
	v_mov_b32_e32 v2, s8
	global_atomic_add v1, v2, s[92:93] offset:1024

;     __device__ __forceinline__ bool next(int i, Unit& u) const {
;         const long Lx = (long)i * G + c; if (Lx >= nrun) return false;
;         map((int)Lx, u); return true;
;     }
; __global__ void __launch_bounds__(NTHR) mega(Params p) {
;     ...
;     if (IN(4)) {
;         const bool split = (gridDim.x == 256);
;         pg8::Gemm g{(const bf16_t*)(ws + WS_GATE), (const bf16_t*)(ws + WS_WOUTE), T, 1024, 2048, 2048};
;         pg8::StaticOrder S; S.init(T, 1024, gridDim.x, blockIdx.x, split ? 512 : -1);
;         EpiOutResB E{(bf16_t*)(ws + WS_XB), (float*)(ws + WS_RSQ1)};
;         pg8::gemm_phase<EpiOutResB, pg8::StaticOrder>(L, g, S, E);
.Lp4_reenter:
	s_movk_i32 s100, 0x44
	s_cmpk_eq_i32 s94, 0x100
	s_cselect_b32 s100, 0x40, s100
	s_cmpk_eq_i32 s94, 0x100
	s_cselect_b64 s[0:1], -1, 0
	s_movk_i32 s3, 0x200
	s_and_b64 s[4:5], s[0:1], exec
	s_cselect_b32 s14, s3, 0x220
	s_cmp_eq_u32 s101, 1
	s_cbranch_scc0 .Lp4_nrun_ok
	s_add_i32 s14, s2, 1
.Lp4_nrun_ok:
	s_cmp_lt_i32 s2, s14
	s_cselect_b64 s[4:5], -1, 0
	s_cmp_ge_i32 s2, s14
	v_readfirstlane_b32 s6, v136
	s_cbranch_scc1 .LBB0_673
	s_ashr_i32 s3, s2, 31
	s_lshr_b32 s3, s3, 29
	s_add_i32 s3, s2, s3
	s_and_b32 s7, s3, -8
	s_sub_i32 s7, s2, s7
	s_cmp_lt_i32 s7, 0
	s_movk_i32 s10, 0x45
	s_cselect_b32 s10, s10, s100
	s_mul_i32 s7, s7, s10
	s_ashr_i32 s3, s3, 3
	s_add_i32 s3, s7, s3
	s_ashr_i32 s7, s3, 31
	s_lshr_b32 s7, s7, 27
	s_add_i32 s7, s3, s7
	s_ashr_i32 s10, s7, 5
	s_andn2_b32 s7, s7, 31
	s_sub_i32 s3, s3, s7
	s_bfe_i32 s7, s3, 0x80000
	s_bfe_u32 s7, s7, 0x3000c
	s_add_i32 s7, s3, s7
	s_bfe_i32 s11, s7, 0x80000
	s_and_b32 s7, s7, 0xf8
	s_sub_i32 s3, s3, s7
	s_lshl_b32 s10, s10, 3
	s_sext_i32_i16 s11, s11
	s_sext_i32_i8 s3, s3
	s_add_i32 s36, s10, s3
	s_ashr_i32 s34, s11, 3

;     __device__ __forceinline__ bool next(int i, Unit& u) const {
;         const long Lx = (long)i * G + c; if (Lx >= nrun) return false;
;         map((int)Lx, u); return true;
; template <class Epi, class Sched>
; __device__ __forceinline__ void gemm_phase(LAS unsigned char* lds, const Gemm g, const Sched& S, const Epi& E) {
;     ...
;         const bool has_next = S.next(ui + 1, nxt);
;         const char* nA = has_next ? (const char*)g.A + (size_t)nxt.pm * tstep + nxt.koff : cA; const char* nB = has_next ? (const char*)g.Bt + (size_t)nxt.pn * tstep + nxt.koff : cB;
.LBB0_679:
	s_add_i32 s15, s15, 1
	s_mul_i32 s6, s15, s64
	s_mul_hi_u32 s7, s15, s65
	s_add_i32 s7, s7, s6
	s_mul_i32 s6, s15, s65
	s_add_u32 s28, s6, s2
	s_addc_u32 s29, s7, s68
	v_cmp_ge_i64_e32 vcc, s[28:29], v[140:141]
	v_cmp_lt_i64_e64 s[6:7], s[28:29], v[140:141]
	s_cbranch_vccnz .LBB0_681
	s_ashr_i32 s24, s28, 31
	s_lshr_b32 s24, s24, 29
	s_add_i32 s24, s28, s24
	s_ashr_i32 s25, s24, 3
	s_and_b32 s24, s24, -8
	s_sub_i32 s24, s28, s24
	s_cmp_lt_i32 s24, 0
	s_cselect_b32 s26, s14, s100
	s_mul_i32 s24, s24, s26
	s_add_i32 s24, s24, s25
	s_ashr_i32 s25, s24, 31
	s_lshr_b32 s25, s25, 27
	s_add_i32 s25, s24, s25
	s_ashr_i32 s26, s25, 5
	s_lshl_b32 s26, s26, 3
	s_sub_i32 s27, 0x88, s26
	s_min_i32 s27, s27, 8
	s_abs_i32 s28, s27
	v_cvt_f32_u32_e32 v0, s28
	s_sub_i32 s30, 0, s28
	s_andn2_b32 s25, s25, 31
	s_sub_i32 s25, s24, s25
	v_rcp_iflag_f32_e32 v0, v0
	s_abs_i32 s24, s25
	s_xor_b32 s29, s25, s27
	s_ashr_i32 s29, s29, 31
	v_mul_f32_e32 v0, 0x4f7ffffe, v0
	v_cvt_u32_f32_e32 v0, v0
	s_nop 0
	v_readfirstlane_b32 s31, v0
	s_mul_i32 s30, s30, s31
	s_mul_hi_u32 s30, s31, s30
	s_add_i32 s31, s31, s30
	s_mul_hi_u32 s30, s24, s31
	s_mul_i32 s31, s30, s28
	s_sub_i32 s24, s24, s31
	s_add_i32 s35, s30, 1
	s_sub_i32 s31, s24, s28
	s_cmp_ge_u32 s24, s28
	s_cselect_b32 s30, s35, s30
	s_cselect_b32 s24, s31, s24
	s_add_i32 s31, s30, 1
	s_cmp_ge_u32 s24, s28
	s_cselect_b32 s24, s31, s30
	s_xor_b32 s24, s24, s29
	s_sub_i32 s24, s24, s29
	s_mul_i32 s27, s24, s27
	s_sub_i32 s25, s25, s27
	s_add_i32 s26, s26, s25

; __global__ void __launch_bounds__(NTHR) mega(Params p) {
;     ...
;         if (split) {
;             pg8::Gemm gs{(const bf16_t*)(ws + WS_GATE), (const bf16_t*)(ws + WS_WOUTE), T, 1024, 256, 2048};
;             pg8::SliceOrder SS{S, 512, 8, 512u};
;             EpiPartial EP{(float*)(ws + WS_Q)};
;             pg8::gemm_phase<EpiPartial, pg8::SliceOrder>(L, gs, SS, EP);
;             xcd_barrier(xb);
;             splitk_reduce(S, 512, 8, (const float*)(ws + WS_Q), (bf16_t*)(ws + WS_XB), (float*)(ws + WS_RSQ1));
;         }
;     }
.LBB0_705:
	s_cmp_eq_u32 s101, 1
	s_cbranch_scc1 .Lp4_tail_done

; #define PG8_STAGE(bufoff, gbase, voff) do { _Pragma("unroll") for (int _i = 0; _i < 2; ++_i) \
;         __builtin_amdgcn_global_load_lds((const unsigned*)((const char*)(gbase) + (voff)[_i]), (LAS unsigned*)(lds + (bufoff) + ldsw + _i * 8192), 16, 0, 0); } while (0)
; #define PG8_WAIT_V(n) asm volatile("s_waitcnt vmcnt(" #n ")" ::: "memory")
; #define PG8_BAR __builtin_amdgcn_s_barrier()
; #define SEAM(k) do { if (IN(k) && IN((k) + 1)) xcd_barrier(xb); } while (0)
; template <class Epi, class Sched>
; __device__ __forceinline__ void gemm_phase(LAS unsigned char* lds, const Gemm g, const Sched& S, const Epi& E) {
;     ...
;     Unit cur, nxt; int ui = 0;
;     if (!S.next(0, cur)) return;
;     f32x4 acc[2][2][4][2];
; #pragma unroll
;     for (int a = 0; a < 2; ++a)
; #pragma unroll
;         for (int b = 0; b < 2; ++b)
; #pragma unroll
;             for (int m = 0; m < 4; ++m)
; #pragma unroll
;                 for (int n = 0; n < 2; ++n) acc[a][b][m][n] = (f32x4){0.f, 0.f, 0.f, 0.f};
;     bf16x8 At[4][2], B0[2][2], B1[2][2];
;     const char* cA = (const char*)g.A + (size_t)cur.pm * tstep + cur.koff; const char* cB = (const char*)g.Bt + (size_t)cur.pn * tstep + cur.koff;
;     PG8_STAGE(PG8_SB(0, 0), cB, voffB); PG8_STAGE(PG8_SB(0, 1), cB + hstep, voffB); PG8_STAGE(PG8_SA(0, 0), cA, voffA); PG8_STAGE(PG8_SA(0, 1), cA + hstep, voffA);
;     if (wr == 1) PG8_BAR;
;     PG8_WAIT_V(2); PG8_BAR;
;     PG8_STAGE(PG8_SB(1, 0), cB + kstep, voffB); PG8_STAGE(PG8_SA(1, 0), cA + kstep, voffA); PG8_STAGE(PG8_SB(1, 1), cB + hstep + kstep, voffB);
;     PG8_WAIT_V(6); PG8_BAR;
; __global__ void __launch_bounds__(NTHR) mega(Params p) {
;     ...
;     SEAM(4);
;     if (IN(5)) {
;         pg8::Gemm g{(const bf16_t*)(ws + WS_XB), (const bf16_t*)(ws + WS_WINO), T, 3072, 1024, 1024};
;         pg8::StaticOrder S; S.init(T, 3072, gridDim.x, blockIdx.x);
;         EpiInOdd E{(bf16_t*)(ws + WS_Z2), (const float*)(ws + WS_RSQ1)};
;         pg8::gemm_phase<EpiInOdd, pg8::StaticOrder>(L, g, S, E);
.Lp5_entry:
	s_cmpk_eq_i32 s94, 0x100
	s_cbranch_scc0 .Lp5_go
	s_cmp_lg_u32 s101, 0
	s_cbranch_scc1 .Lp5_go
	s_sub_i32 s3, s2, 0x60
	s_cmp_lt_u32 s3, 32
	s_cbranch_scc0 .Lp5_go
	s_mov_b32 s99, s2
	s_lshl_b32 s2, s3, 3
	s_add_i32 s2, s2, 0x1000
	s_mov_b32 s101, 1
	s_branch .Lp4_reenter
.Lp4_tail_done:
	s_mov_b32 s2, s99
	s_mov_b32 s101, 2
	v_cmp_eq_u32_e32 vcc, 0, v136
	s_and_saveexec_b64 s[4:5], vcc
	s_cbranch_execz .Lp4_sig_skip
	buffer_wbl2 sc1
	s_waitcnt vmcnt(0)
	s_add_u32 s6, s44, 0x1f711800
	s_addc_u32 s7, s45, 0
	v_mov_b32_e32 v0, 0
	v_mov_b32_e32 v1, 1
	global_atomic_add v0, v1, s[6:7]
	s_waitcnt vmcnt(0)
.Lp4_sig_skip:
	s_or_b64 exec, exec, s[4:5]
	s_branch .Lp5_entry
.Lp5_go:
	s_cmpk_gt_i32 s2, 0x65f
	v_readfirstlane_b32 s5, v136
	s_cbranch_scc1 .LBB0_841
	v_lshrrev_b32_e32 v0, 5, v136
	v_lshrrev_b32_e32 v2, 1, v136
	v_and_b32_e32 v0, 4, v0
	s_waitcnt lgkmcnt(0)
	v_bfe_u32 v1, v136, 2, 2
	v_and_b32_e32 v11, 24, v2
	v_or3_b32 v0, v0, v1, v11
	v_lshlrev_b32_e32 v1, 4, v136
	v_add_u32_e32 v8, 0x2000, v1
	v_lshrrev_b32_e32 v2, 7, v8
	s_movk_i32 s0, 0xe0
	v_and_b32_e32 v4, 32, v136
	s_add_u32 s3, s44, 0x1a20000
	v_and_or_b32 v3, v2, s0, v0
	v_bitop3_b32 v9, v1, v4, 48 bitop3:0x6c
	v_and_b32_e32 v10, 64, v136
	v_bfe_u32 v12, v136, 2, 4
	s_movk_i32 s0, 0xf0
	s_addc_u32 s33, s45, 0
	v_or_b32_e32 v1, v9, v10
	v_and_or_b32 v2, v2, s0, v12
	s_add_u32 s34, s44, 0x1000000
	v_lshl_or_b32 v130, v2, 11, v1
	v_lshrrev_b32_e32 v2, 3, v136
	s_movk_i32 s0, 0x60
	s_addc_u32 s35, s45, 0
	v_and_or_b32 v0, v2, s0, v0
	s_movk_i32 s0, 0x70
	s_ashr_i32 s37, s2, 31
	v_lshl_or_b32 v132, v0, 11, v1
	v_and_or_b32 v0, v2, s0, v12
	s_lshr_b32 s0, s37, 29
	s_add_i32 s0, s2, s0
	s_lshr_b32 s16, s5, 6
	s_and_b32 s1, s0, -8
	s_lshr_b32 s18, s5, 8
	s_lshl_b32 s36, s16, 10
	s_sub_i32 s1, s2, s1
	s_cmp_lt_i32 s1, 0
	s_movk_i32 s38, 0xcd
	s_cselect_b32 s4, s38, 0xcc
	s_mul_i32 s1, s1, s4
	s_ashr_i32 s0, s0, 3
	s_add_i32 s1, s1, s0
	s_mul_hi_i32 s0, s1, 0x2aaaaaab
	s_lshr_b32 s4, s0, 31
	s_ashr_i32 s0, s0, 4
	s_add_i32 s0, s0, s4
	s_lshl_b32 s6, s0, 3
	s_mulk_i32 s0, 0x60
	s_sub_i32 s0, s1, s0
	s_bfe_i32 s1, s0, 0x80000
	s_bfe_u32 s1, s1, 0x3000c
	s_add_i32 s1, s0, s1
	s_bfe_i32 s4, s1, 0x80000
	s_and_b32 s1, s1, 0xf8
	s_sub_i32 s0, s0, s1
	s_sext_i32_i16 s4, s4
	s_sext_i32_i8 s0, s0
	s_lshr_b32 s4, s4, 3
	s_add_i32 s0, s6, s0
	s_ashr_i32 s1, s0, 31
	s_bfe_i64 s[10:11], s[4:5], 0x100000
	s_lshl_b64 s[6:7], s[0:1], 19
	s_lshl_b64 s[10:11], s[10:11], 19
	s_add_u32 s28, s34, s10
	s_addc_u32 s29, s35, s11
	s_add_i32 s39, s36, 0
	s_add_i32 m0, s39, 0x10000
	v_lshl_or_b32 v128, v3, 11, v1
	global_load_lds_dwordx4 v132, s[28:29]
	s_add_i32 m0, s39, 0x12000
	s_add_u32 s10, s28, 0x40000
	global_load_lds_dwordx4 v128, s[28:29]
	s_addc_u32 s11, s29, 0
	s_add_i32 m0, s39, 0x14000
	v_lshl_or_b32 v134, v0, 11, v1
	global_load_lds_dwordx4 v132, s[10:11]
	s_add_i32 m0, s39, 0x16000
	s_add_u32 s6, s3, s6
	s_addc_u32 s7, s33, s7
	s_add_i32 s48, s39, 0x2000
	global_load_lds_dwordx4 v128, s[10:11]
	s_mov_b32 m0, s39
	s_add_u32 s10, s6, 0x40000
	global_load_lds_dwordx4 v134, s[6:7]
	s_mov_b32 m0, s48
	s_addc_u32 s11, s7, 0
	s_add_i32 s49, s39, 0x4000
	global_load_lds_dwordx4 v130, s[6:7]
	s_mov_b32 m0, s49
	s_add_i32 s50, s39, 0x6000
	global_load_lds_dwordx4 v134, s[10:11]
	s_mov_b32 m0, s50
	v_mov_b32_e32 v133, 0
	global_load_lds_dwordx4 v130, s[10:11]
	v_mov_b32_e32 v129, v133
	v_mov_b32_e32 v135, v133
	v_mov_b32_e32 v131, v133
	s_cmp_eq_u32 s18, 1
	s_mov_b32 s51, 0
	v_lshl_add_u64 v[6:7], s[28:29], 0, v[132:133]
	v_lshl_add_u64 v[4:5], s[28:29], 0, v[128:129]
	v_lshl_add_u64 v[0:1], s[6:7], 0, v[134:135]
	s_cselect_b64 s[10:11], -1, 0
	s_cmp_lg_u32 s18, 1
	v_lshl_add_u64 v[2:3], s[6:7], 0, v[130:131]
	s_cbranch_scc1 .LBB0_828
	s_barrier
.LBB0_828:
	s_add_u32 s12, s44, 0x5f0e000
	s_addc_u32 s13, s45, 0
	s_add_u32 s14, s44, 0x5e42000
	s_addc_u32 s15, s45, 0
	s_lshl_b32 s1, s16, 5
	s_mov_b64 s[16:17], 0x80
	s_and_b32 s22, s1, 0x60
	s_add_i32 m0, s39, 0x18000
	v_lshl_add_u64 v[6:7], v[6:7], 0, s[16:17]
	s_lshl_b32 s19, s18, 13
	s_lshl_b32 s23, s22, 7
	s_waitcnt vmcnt(2)
	s_barrier
	global_load_lds_dwordx4 v[6:7], off
	v_lshl_add_u64 v[4:5], v[4:5], 0, s[16:17]
	s_add_i32 m0, s39, 0x1a000
	s_add_i32 s52, s39, 0x8000
	s_add_i32 s53, s39, 0xa000
	global_load_lds_dwordx4 v[4:5], off
	v_lshl_add_u64 v[0:1], v[0:1], 0, s[16:17]
	s_mov_b32 m0, s52
	s_add_u32 s20, s28, 0x40080
	global_load_lds_dwordx4 v[0:1], off
	v_lshl_add_u64 v[0:1], v[2:3], 0, s[16:17]
	s_mov_b32 m0, s53
	s_addc_u32 s21, s29, 0
	global_load_lds_dwordx4 v[0:1], off
	s_add_i32 m0, s39, 0x1c000
	v_lshl_add_u64 v[0:1], s[20:21], 0, v[132:133]
	global_load_lds_dwordx4 v[0:1], off
	v_lshl_add_u64 v[0:1], s[20:21], 0, v[128:129]
	s_add_i32 m0, s39, 0x1e000
	s_sext_i32_i8 s1, s4
	global_load_lds_dwordx4 v[0:1], off
	v_and_b32_e32 v0, 15, v136
	v_lshlrev_b32_e32 v1, 1, v11
	v_lshlrev_b32_e32 v2, 2, v136
	v_lshlrev_b32_e32 v3, 6, v136
	s_movk_i32 s4, 0x3c0
	v_lshl_or_b32 v137, s18, 6, v0
	v_lshl_or_b32 v0, v0, 6, v1
	v_and_b32_e32 v2, 32, v2
	v_and_or_b32 v1, v3, s4, v1
	v_bitop3_b32 v152, s23, v1, v2 bitop3:0xf6
	v_lshlrev_b32_e32 v1, 8, v136
	v_bitop3_b32 v0, v0, s19, v2 bitop3:0xde
	v_and_b32_e32 v1, 0x38000, v1
	v_lshlrev_b32_e32 v2, 11, v12
	v_or3_b32 v1, v9, v1, v2
	v_add_u32_e32 v138, v1, v10
	v_lshlrev_b32_e32 v1, 4, v8
	s_waitcnt vmcnt(6)
	s_cmpk_lt_u32 s5, 0x100
	v_and_b32_e32 v1, 0x78000, v1
	s_cselect_b64 s[18:19], -1, 0
	v_or3_b32 v1, v9, v1, v2
	s_add_i32 s56, 0, 0x10000
	s_add_i32 s57, 0, 0x14000
	s_ashr_i32 s54, s94, 31
	s_mov_b32 s55, s94
	v_or_b32_e32 v153, s22, v11
	v_mov_b32_e32 v139, v133
	v_add_u32_e32 v140, v1, v10
	v_mov_b32_e32 v141, v133
	s_movk_i32 s30, 0x660
	s_cmpk_eq_i32 s94, 0x100
	s_cbranch_scc0 .Lp5_bound_done
	s_sub_i32 s31, s2, 0x60
	s_cmp_lt_u32 s31, 32
	s_cselect_b32 s30, 0x560, s30
	s_sub_i32 s31, s2, 0x80
	s_cmp_lt_u32 s31, 32
	s_cselect_b32 s30, 0x6a0, s30
.Lp5_bound_done:
	s_add_i32 s31, s30, -1
	v_mov_b32_e32 v142, s30
	v_mov_b32_e32 v143, 0
	v_mov_b32_e32 v144, s31
	v_mov_b32_e32 v145, 0
	v_add_u32_e32 v154, s56, v152
	v_add_u32_e32 v155, s57, v152
	v_add_u32_e32 v156, 0, v0
	v_mov_b32_e32 v157, 0x358637bd
	s_mov_b32 s58, 0x800000
	s_movk_i32 s59, 0x1800
	s_barrier
	s_branch .LBB0_831

;     __device__ __forceinline__ bool next(int i, Unit& u) const {
;         const long Lx = (long)i * G + c; if (Lx >= nrun) return false;
;         map((int)Lx, u); return true;
;     }
; template <class Epi, class Sched>
; __device__ __forceinline__ void gemm_phase(LAS unsigned char* lds, const Gemm g, const Sched& S, const Epi& E) {
;     ...
;         const bool has_next = S.next(ui + 1, nxt);
;         const char* nA = has_next ? (const char*)g.A + (size_t)nxt.pm * tstep + nxt.koff : cA; const char* nB = has_next ? (const char*)g.Bt + (size_t)nxt.pn * tstep + nxt.koff : cB;
;         for (int t = 0; t < nt; t += 2) {
;             const bool last = (t == nt - 2);
;             const char* a1 = cA + (size_t)(t + 1) * kstep;
;             const char* a2 = last ? nA : cA + (size_t)(t + 2) * kstep; const char* b2 = last ? nB : cB + (size_t)(t + 2) * kstep;
;             const char* a3 = a2 + kstep; const char* b3 = b2 + kstep;
;             PG8_LDB(B0, 0, 0); PG8_LDB(B1, 0, 1); PG8_SCHED; PG8_LDA(At, 0, 0); PG8_STAGE(PG8_SA(1, 1), a1 + hstep, voffA);
;             PG8_WAIT_V(8); PG8_WAIT_L(0); PG8_BAR; PG8_MMA(0, 0, At, B0); PG8_MMA(0, 1, At, B1); PG8_BAR; PG8_SCHED;
;             PG8_LDA(At, 0, 1); PG8_STAGE(PG8_SB(0, 0), b2, voffB); PG8_STAGE(PG8_SB(0, 1), b2 + hstep, voffB); PG8_STAGE(PG8_SA(0, 0), a2, voffA);
;             PG8_WAIT_V(8); PG8_WAIT_L(0); PG8_BAR; PG8_MMA(1, 0, At, B0); PG8_MMA(1, 1, At, B1); PG8_BAR; PG8_SCHED;
;             PG8_LDB(B0, 1, 0); PG8_LDB(B1, 1, 1); PG8_SCHED; PG8_LDA(At, 1, 0); PG8_STAGE(PG8_SA(0, 1), a2 + hstep, voffA);
;             PG8_WAIT_V(8); PG8_WAIT_L(0); PG8_BAR; PG8_MMA(0, 0, At, B0); PG8_MMA(0, 1, At, B1); PG8_BAR; PG8_SCHED;
;             PG8_LDA(At, 1, 1); PG8_STAGE(PG8_SB(1, 0), b3, voffB); PG8_STAGE(PG8_SB(1, 1), b3 + hstep, voffB); PG8_STAGE(PG8_SA(1, 0), a3, voffA);
;             PG8_WAIT_V(8); PG8_WAIT_L(0); PG8_BAR; PG8_MMA(1, 0, At, B0); PG8_MMA(1, 1, At, B1); PG8_BAR; PG8_SCHED;
;         }
;         if (wr == 0) PG8_BAR;
;         E(acc, cur, wr, wc, fr, fq);
;         if (!has_next) break;
; #pragma unroll
;         for (int a = 0; a < 2; ++a)
; #pragma unroll
;             for (int b = 0; b < 2; ++b)
; #pragma unroll
;                 for (int m = 0; m < 4; ++m)
; #pragma unroll
;                     for (int n = 0; n < 2; ++n) acc[a][b][m][n] = (f32x4){0.f, 0.f, 0.f, 0.f};
.LBB0_831:
	s_add_i32 s51, s51, 1
	s_mul_i32 s4, s51, s54
	s_mul_hi_u32 s5, s51, s55
	s_add_i32 s5, s5, s4
	s_mul_i32 s4, s51, s55
	s_add_u32 s24, s4, s2
	s_addc_u32 s25, s5, s37
	v_cmp_gt_i64_e32 vcc, s[24:25], v[144:145]
	v_cmp_lt_i64_e64 s[4:5], s[24:25], v[142:143]
	s_cbranch_vccnz .LBB0_833
	s_cmpk_lt_i32 s24, 0x660
	s_cbranch_scc1 .Lp5_noremap
	s_sub_i32 s24, s24, 0x120
.Lp5_noremap:
	s_ashr_i32 s20, s24, 31
	s_lshr_b32 s20, s20, 29
	s_add_i32 s20, s24, s20
	s_ashr_i32 s21, s20, 3
	s_and_b32 s20, s20, -8
	s_sub_i32 s20, s24, s20
	s_cmp_lt_i32 s20, 0
	s_cselect_b32 s22, s38, 0xcc
	s_mul_i32 s20, s20, s22
	s_add_i32 s20, s20, s21
	s_mul_hi_i32 s21, s20, 0x2aaaaaab
	s_lshr_b32 s22, s21, 31
	s_ashr_i32 s21, s21, 4
	s_add_i32 s21, s21, s22
	s_lshl_b32 s22, s21, 3
	s_sub_i32 s23, 0x88, s22
	s_min_i32 s23, s23, 8
	s_abs_i32 s24, s23
	v_cvt_f32_u32_e32 v0, s24
	s_sub_i32 s26, 0, s24
	s_mulk_i32 s21, 0x60
	s_sub_i32 s21, s20, s21
	v_rcp_iflag_f32_e32 v0, v0
	s_abs_i32 s20, s21
	s_xor_b32 s25, s21, s23
	s_ashr_i32 s25, s25, 31
	v_mul_f32_e32 v0, 0x4f7ffffe, v0
	v_cvt_u32_f32_e32 v0, v0
	s_nop 0
	v_readfirstlane_b32 s27, v0
	s_mul_i32 s26, s26, s27
	s_mul_hi_u32 s26, s27, s26
	s_add_i32 s27, s27, s26
	s_mul_hi_u32 s26, s20, s27
	s_mul_i32 s27, s26, s24
	s_sub_i32 s20, s20, s27
	s_add_i32 s30, s26, 1
	s_sub_i32 s27, s20, s24
	s_cmp_ge_u32 s20, s24
	s_cselect_b32 s26, s30, s26
	s_cselect_b32 s20, s27, s20
	s_add_i32 s27, s26, 1
	s_cmp_ge_u32 s20, s24
	s_cselect_b32 s20, s27, s26
	s_xor_b32 s20, s20, s25
	s_sub_i32 s20, s20, s25
	s_mul_i32 s23, s20, s23
	s_sub_i32 s21, s21, s23
	s_add_i32 s22, s22, s21
	s_cmpk_lt_i32 s22, 0x80
	s_cbranch_scc1 .Lp5_nowait
	s_cmpk_eq_i32 s94, 0x100
	s_cbranch_scc0 .Lp5_nowait
	s_add_u32 s26, s44, 0x1f711800
	s_addc_u32 s27, s45, 0
	v_mov_b32_e32 v0, 0
.Lp5_poll:
	global_load_dword v1, v0, s[26:27] sc1
	s_waitcnt vmcnt(0)
	v_readfirstlane_b32 s24, v1
	s_cmp_ge_u32 s24, 32
	s_cbranch_scc1 .Lp5_polled
	s_sleep 8
	s_branch .Lp5_poll
.Lp5_polled:
	buffer_inv sc1
	s_waitcnt vmcnt(0)
.Lp5_nowait:
.LBB0_833:
	s_ashr_i32 s23, s22, 31
	s_lshl_b64 s[24:25], s[22:23], 19
	s_add_u32 s24, s3, s24
	s_addc_u32 s25, s33, s25
	s_and_b64 s[26:27], s[4:5], exec
	s_cselect_b32 s23, s25, s7
	s_cselect_b32 s64, s24, s6
	s_ashr_i32 s21, s20, 31
	s_lshl_b64 s[26:27], s[20:21], 19
	s_add_u32 s26, s34, s26
	s_addc_u32 s27, s35, s27
	s_and_b64 s[30:31], s[4:5], exec
	s_cselect_b32 s21, s27, s29
	s_cselect_b32 s65, s26, s28
	s_add_u32 s6, s6, 0x40080
	s_addc_u32 s7, s7, 0
	s_add_u32 s68, s28, 0x100
	v_mov_b32_e32 v0, 0
	s_addc_u32 s69, s29, 0
	s_mov_b32 s74, -2
	v_mov_b32_e32 v1, v0
	v_mov_b32_e32 v2, v0
	v_mov_b32_e32 v3, v0
	v_mov_b32_e32 v4, v0
	v_mov_b32_e32 v5, v0
	v_mov_b32_e32 v6, v0
	v_mov_b32_e32 v7, v0
	v_mov_b32_e32 v16, v0
	v_mov_b32_e32 v17, v0
	v_mov_b32_e32 v18, v0
	v_mov_b32_e32 v19, v0
	v_mov_b32_e32 v20, v0
	v_mov_b32_e32 v21, v0
	v_mov_b32_e32 v22, v0
	v_mov_b32_e32 v23, v0
	v_mov_b32_e32 v32, v0
	v_mov_b32_e32 v33, v0
	v_mov_b32_e32 v34, v0
	v_mov_b32_e32 v35, v0
	v_mov_b32_e32 v36, v0
	v_mov_b32_e32 v37, v0
	v_mov_b32_e32 v38, v0
	v_mov_b32_e32 v39, v0
	s_waitcnt vmcnt(0)
	v_mov_b32_e32 v48, v0
	v_mov_b32_e32 v49, v0
	v_mov_b32_e32 v50, v0
	v_mov_b32_e32 v51, v0
	v_mov_b32_e32 v52, v0
	v_mov_b32_e32 v53, v0
	v_mov_b32_e32 v54, v0
	v_mov_b32_e32 v55, v0
	v_mov_b32_e32 v8, v0
	v_mov_b32_e32 v9, v0
	v_mov_b32_e32 v10, v0
	v_mov_b32_e32 v11, v0
	v_mov_b32_e32 v12, v0
	v_mov_b32_e32 v13, v0
	v_mov_b32_e32 v14, v0
	v_mov_b32_e32 v15, v0
	v_mov_b32_e32 v24, v0
	v_mov_b32_e32 v25, v0
	v_mov_b32_e32 v26, v0
	v_mov_b32_e32 v27, v0
	v_mov_b32_e32 v28, v0
	v_mov_b32_e32 v29, v0
	v_mov_b32_e32 v30, v0
	v_mov_b32_e32 v31, v0
	v_mov_b32_e32 v40, v0
	v_mov_b32_e32 v41, v0
	v_mov_b32_e32 v42, v0
	v_mov_b32_e32 v43, v0
	v_mov_b32_e32 v44, v0
	v_mov_b32_e32 v45, v0
	v_mov_b32_e32 v46, v0
	v_mov_b32_e32 v47, v0
	v_mov_b32_e32 v56, v0
	v_mov_b32_e32 v57, v0
	v_mov_b32_e32 v58, v0
	v_mov_b32_e32 v59, v0
	v_mov_b32_e32 v60, v0
	v_mov_b32_e32 v61, v0
	v_mov_b32_e32 v62, v0
	v_mov_b32_e32 v63, v0
	v_mov_b32_e32 v64, v0
	v_mov_b32_e32 v65, v0
	v_mov_b32_e32 v66, v0
	v_mov_b32_e32 v67, v0
	v_mov_b32_e32 v68, v0
	v_mov_b32_e32 v69, v0
	v_mov_b32_e32 v70, v0
	v_mov_b32_e32 v71, v0
	v_mov_b32_e32 v80, v0
	v_mov_b32_e32 v81, v0
	v_mov_b32_e32 v82, v0
	v_mov_b32_e32 v83, v0
	v_mov_b32_e32 v84, v0
	v_mov_b32_e32 v85, v0
	v_mov_b32_e32 v86, v0
	v_mov_b32_e32 v87, v0
	v_mov_b32_e32 v88, v0
	v_mov_b32_e32 v89, v0
	v_mov_b32_e32 v90, v0
	v_mov_b32_e32 v91, v0
	v_mov_b32_e32 v92, v0
	v_mov_b32_e32 v93, v0
	v_mov_b32_e32 v94, v0
	v_mov_b32_e32 v95, v0
	v_mov_b32_e32 v96, v0
	v_mov_b32_e32 v97, v0
	v_mov_b32_e32 v98, v0
	v_mov_b32_e32 v99, v0
	v_mov_b32_e32 v104, v0
	v_mov_b32_e32 v105, v0
	v_mov_b32_e32 v106, v0
	v_mov_b32_e32 v107, v0
	v_mov_b32_e32 v72, v0
	v_mov_b32_e32 v73, v0
	v_mov_b32_e32 v74, v0
	v_mov_b32_e32 v75, v0
	v_mov_b32_e32 v76, v0
	v_mov_b32_e32 v77, v0
	v_mov_b32_e32 v78, v0
	v_mov_b32_e32 v79, v0
	v_mov_b32_e32 v100, v0
	v_mov_b32_e32 v101, v0
	v_mov_b32_e32 v102, v0
	v_mov_b32_e32 v103, v0
	v_mov_b32_e32 v108, v0
	v_mov_b32_e32 v109, v0
	v_mov_b32_e32 v110, v0
	v_mov_b32_e32 v111, v0
	v_mov_b32_e32 v112, v0
	v_mov_b32_e32 v113, v0
	v_mov_b32_e32 v114, v0
	v_mov_b32_e32 v115, v0
	v_mov_b32_e32 v116, v0
	v_mov_b32_e32 v117, v0
	v_mov_b32_e32 v118, v0
	v_mov_b32_e32 v119, v0
	v_mov_b32_e32 v120, v0
	v_mov_b32_e32 v121, v0
	v_mov_b32_e32 v122, v0
	v_mov_b32_e32 v123, v0
	v_mov_b32_e32 v124, v0
	v_mov_b32_e32 v125, v0
	v_mov_b32_e32 v126, v0
	v_mov_b32_e32 v127, v0

; __global__ void __launch_bounds__(NTHR) mega(Params p) {
	.amdhsa_kernel _Z4mega6Params
		.amdhsa_group_segment_fixed_size 0
		.amdhsa_private_segment_fixed_size 0
		.amdhsa_kernarg_size 480
		.amdhsa_user_sgpr_count 2
		.amdhsa_user_sgpr_dispatch_ptr 0
		.amdhsa_user_sgpr_queue_ptr 0
		.amdhsa_user_sgpr_kernarg_segment_ptr 1
		.amdhsa_user_sgpr_dispatch_id 0
		.amdhsa_user_sgpr_kernarg_preload_length 0
		.amdhsa_user_sgpr_kernarg_preload_offset 0
		.amdhsa_user_sgpr_private_segment_size 0
		.amdhsa_uses_dynamic_stack 0
		.amdhsa_enable_private_segment 0
		.amdhsa_system_sgpr_workgroup_id_x 1
		.amdhsa_system_sgpr_workgroup_id_y 0
		.amdhsa_system_sgpr_workgroup_id_z 0
		.amdhsa_system_sgpr_workgroup_info 0
		.amdhsa_system_vgpr_workitem_id 2
		.amdhsa_next_free_vgpr 251
		.amdhsa_next_free_sgpr 102
		.amdhsa_accum_offset 252
		.amdhsa_reserve_vcc 1
		.amdhsa_float_round_mode_32 0
		.amdhsa_float_round_mode_16_64 0
		.amdhsa_float_denorm_mode_32 3
		.amdhsa_float_denorm_mode_16_64 3
		.amdhsa_dx10_clamp 1
		.amdhsa_ieee_mode 1
		.amdhsa_fp16_overflow 0
		.amdhsa_tg_split 0
		.amdhsa_exception_fp_ieee_invalid_op 0
		.amdhsa_exception_fp_denorm_src 0
		.amdhsa_exception_fp_ieee_div_zero 0
		.amdhsa_exception_fp_ieee_overflow 0
		.amdhsa_exception_fp_ieee_underflow 0
		.amdhsa_exception_fp_ieee_inexact 0
		.amdhsa_exception_int_div_zero 0
	.end_amdhsa_kernel

; __global__ void __launch_bounds__(NTHR) mega(Params p) {
amdhsa.kernels:
  - .agpr_count:     0
    .args:
      - .offset:         0
        .size:           224
        .value_kind:     by_value
      - .offset:         224
        .size:           4
        .value_kind:     hidden_block_count_x
      - .offset:         228
        .size:           4
        .value_kind:     hidden_block_count_y
      - .offset:         232
        .size:           4
        .value_kind:     hidden_block_count_z
      - .offset:         236
        .size:           2
        .value_kind:     hidden_group_size_x
      - .offset:         238
        .size:           2
        .value_kind:     hidden_group_size_y
      - .offset:         240
        .size:           2
        .value_kind:     hidden_group_size_z
      - .offset:         242
        .size:           2
        .value_kind:     hidden_remainder_x
      - .offset:         244
        .size:           2
        .value_kind:     hidden_remainder_y
      - .offset:         246
        .size:           2
        .value_kind:     hidden_remainder_z
      - .offset:         264
        .size:           8
        .value_kind:     hidden_global_offset_x
      - .offset:         272
        .size:           8
        .value_kind:     hidden_global_offset_y
      - .offset:         280
        .size:           8
        .value_kind:     hidden_global_offset_z
      - .offset:         288
        .size:           2
        .value_kind:     hidden_grid_dims
      - .offset:         312
        .size:           8
        .value_kind:     hidden_multigrid_sync_arg
      - .offset:         344
        .size:           4
        .value_kind:     hidden_dynamic_lds_size
    .group_segment_fixed_size: 0
    .kernarg_segment_align: 8
    .kernarg_segment_size: 480
    .language:       OpenCL C
    .language_version:
      - 2
      - 0
    .max_flat_workgroup_size: 512
    .name:           _Z4mega6Params
    .private_segment_fixed_size: 0
    .sgpr_count:     108
    .sgpr_spill_count: 58
    .symbol:         _Z4mega6Params.kd
    .uniform_work_group_size: 1
    .uses_dynamic_stack: false
    .vgpr_count:     251
    .vgpr_spill_count: 0
    .wavefront_size: 64
